# attention cross-half max via v_permlane32_swap (no LDS round trip); P0 W_out/W_pq transposes with all 24 loads in flight
# speedup vs baseline: 1.0103x; 1.0103x over previous
; DEVI uint32_t pk(float a, float b) { const hwf32x2 v = {a, b}; return __builtin_bit_cast(uint32_t, __builtin_convertvector(v, hwbf16x2)); }
; __device__ void phase_prep(const P& p, int vb, int nvb) {
;     ...
;   {
;     uint16_t* o = (uint16_t*)(ws + WS_WT_OUT); const float* w = p.in[14]; const float* ga = p.in[12]; const float* gc = p.in[13];
;     for (size_t i = gid; i < (size_t)512 * 1024; i += gsz) {
;       const int k = 2 * (int)(i >> 10), n = (int)(i & 1023);
;       const float g0 = k < 512 ? ga[k] : gc[k - 512], g1 = k < 512 ? ga[k + 1] : gc[k + 1 - 512];
;       *(uint32_t*)(o + (size_t)n * 1024 + k) = pk(w[(size_t)k * 1024 + n] * g0, w[(size_t)(k + 1) * 1024 + n] * g1);
;     }
;   }
;   {
;     uint16_t* o = (uint16_t*)(ws + WS_WT_PQ); const float* w = p.in[16]; const float* g = p.in[15];
;     for (size_t i = gid; i < (size_t)512 * 1024; i += gsz) {
;       const int k = 2 * (int)(i >> 10), n = (int)(i & 1023);
;       *(uint32_t*)(o + (size_t)n * 1024 + k) = pk(w[(size_t)k * 1024 + n] * g[k], w[(size_t)(k + 1) * 1024 + n] * g[k + 1]);
;     }
;   }
.LBB0_21:
	v_writelane_b32 v248, s18, 4
	s_nop 1
	v_writelane_b32 v248, s19, 5
	v_writelane_b32 v248, s16, 6
	s_nop 1
	v_writelane_b32 v248, s17, 7
	s_or_b64 exec, exec, s[0:1]
	s_add_u32 s22, s80, 0x3a0000
	s_addc_u32 s23, s81, 0
	s_waitcnt lgkmcnt(0)
	s_add_u32 s64, s80, 0x5a0000
	s_mov_b64 s[0:1], 0x80000
	s_addc_u32 s65, s81, 0
	v_cmp_gt_u64_e32 vcc, s[0:1], v[6:7]
	s_and_saveexec_b64 s[0:1], vcc
	s_cbranch_execz .LBB0_26
	v_and_b32_e32 v200, 0x3ff, v6
	v_lshrrev_b32_e32 v201, 10, v6
	v_lshlrev_b32_e32 v202, 2, v200
	v_lshlrev_b32_e32 v203, 3, v201
	v_lshl_add_u32 v204, v201, 13, v202
	v_add_u32_e32 v205, 0x1000, v204
	v_lshlrev_b32_e32 v206, 2, v201
	v_lshl_add_u32 v206, v202, 9, v206
	global_load_dword v208, v204, s[56:57]
	global_load_dword v209, v205, s[56:57]
	global_load_dwordx2 v[224:225], v203, s[52:53]
	s_add_u32 s4, s56, 0x100000
	s_addc_u32 s5, s57, 0
	global_load_dword v210, v204, s[4:5]
	global_load_dword v211, v205, s[4:5]
	global_load_dwordx2 v[226:227], v203, s[52:53] offset:1024
	s_add_u32 s4, s56, 0x200000
	s_addc_u32 s5, s57, 0
	global_load_dword v212, v204, s[4:5]
	global_load_dword v213, v205, s[4:5]
	global_load_dwordx2 v[228:229], v203, s[54:55]
	s_add_u32 s4, s56, 0x300000
	s_addc_u32 s5, s57, 0
	global_load_dword v214, v204, s[4:5]
	global_load_dword v215, v205, s[4:5]
	global_load_dwordx2 v[230:231], v203, s[54:55] offset:1024
	global_load_dword v216, v204, s[84:85]
	global_load_dword v217, v205, s[84:85]
	global_load_dwordx2 v[232:233], v203, s[58:59]
	s_add_u32 s4, s84, 0x100000
	s_addc_u32 s5, s85, 0
	global_load_dword v218, v204, s[4:5]
	global_load_dword v219, v205, s[4:5]
	global_load_dwordx2 v[234:235], v203, s[58:59] offset:1024
	s_add_u32 s4, s84, 0x200000
	s_addc_u32 s5, s85, 0
	global_load_dword v220, v204, s[4:5]
	global_load_dword v221, v205, s[4:5]
	global_load_dwordx2 v[236:237], v203, s[58:59] offset:2048
	s_add_u32 s4, s84, 0x300000
	s_addc_u32 s5, s85, 0
	global_load_dword v222, v204, s[4:5]
	global_load_dword v223, v205, s[4:5]
	global_load_dwordx2 v[238:239], v203, s[58:59] offset:3072
	s_waitcnt vmcnt(21)
	v_pk_mul_f32 v[208:209], v[208:209], v[224:225]
	s_nop 0
	v_cvt_pk_bf16_f32 v208, v208, v209
	global_store_dword v206, v208, s[22:23]
	s_waitcnt vmcnt(19)
	v_pk_mul_f32 v[210:211], v[210:211], v[226:227]
	s_nop 0
	v_cvt_pk_bf16_f32 v210, v210, v211
	global_store_dword v206, v210, s[22:23] offset:512
	s_waitcnt vmcnt(17)
	v_pk_mul_f32 v[212:213], v[212:213], v[228:229]
	s_nop 0
	v_cvt_pk_bf16_f32 v212, v212, v213
	global_store_dword v206, v212, s[22:23] offset:1024
	s_waitcnt vmcnt(15)
	v_pk_mul_f32 v[214:215], v[214:215], v[230:231]
	s_nop 0
	v_cvt_pk_bf16_f32 v214, v214, v215
	global_store_dword v206, v214, s[22:23] offset:1536
	s_waitcnt vmcnt(13)
	v_pk_mul_f32 v[216:217], v[216:217], v[232:233]
	s_nop 0
	v_cvt_pk_bf16_f32 v216, v216, v217
	global_store_dword v206, v216, s[64:65]
	s_waitcnt vmcnt(11)
	v_pk_mul_f32 v[218:219], v[218:219], v[234:235]
	s_nop 0
	v_cvt_pk_bf16_f32 v218, v218, v219
	global_store_dword v206, v218, s[64:65] offset:512
	s_waitcnt vmcnt(9)
	v_pk_mul_f32 v[220:221], v[220:221], v[236:237]
	s_nop 0
	v_cvt_pk_bf16_f32 v220, v220, v221
	global_store_dword v206, v220, s[64:65] offset:1024
	s_waitcnt vmcnt(7)
	v_pk_mul_f32 v[222:223], v[222:223], v[238:239]
	s_nop 0
	v_cvt_pk_bf16_f32 v222, v222, v223
	global_store_dword v206, v222, s[64:65] offset:1536

; __device__ void phase_attn(const P& p, int vb, int nvb, char* smem) {
;     ...
;         float mxa = __builtin_fmaxf(__builtin_fmaxf(s0[0], s0[1]), s0[2]);
;         float mxb = __builtin_fmaxf(__builtin_fmaxf(s1[0], s1[1]), s1[2]);
; #pragma unroll
;         for (int r = 3; r < 15; r += 2) {
;           mxa = __builtin_fmaxf(__builtin_fmaxf(mxa, s0[r]), s0[r + 1]);
;           mxb = __builtin_fmaxf(__builtin_fmaxf(mxb, s1[r]), s1[r + 1]);
;         }
;         float mx = __builtin_fmaxf(__builtin_fmaxf(mxa, s0[15]), __builtin_fmaxf(mxb, s1[15]));
;         mx = fmaxf(mx, __shfl_xor(mx, 32));
;         const float mn = fmaxf(m, mx);
;         const float alpha = __builtin_amdgcn_exp2f(m - mn);
;         const bool moved = __builtin_amdgcn_ballot_w64(mn > m) != 0ull;
;         m = mn;
;         float psum = 0.f;
; #pragma unroll
;         for (int r = 0; r < 16; r++) {
;           s0[r] = __builtin_amdgcn_exp2f(s0[r] - mn); s1[r] = __builtin_amdgcn_exp2f(s1[r] - mn);
;           psum += s0[r] + s1[r];
;         }
;         l = l * alpha + psum;
;         if (moved) { o0 *= alpha; o1 *= alpha; }
.LBB0_290:
	s_or_b64 exec, exec, s[42:43]
	s_nop 8
	v_max_f32_e32 v147, v33, v33
	v_max_f32_e32 v150, v32, v32
	v_max_f32_e32 v147, v150, v147
	v_max3_f32 v126, v48, v49, v50
	v_max3_f32 v147, v147, v34, v35
	v_max3_f32 v126, v126, v51, v52
	v_max3_f32 v147, v147, v36, v37
	v_max3_f32 v126, v126, v53, v54
	v_max3_f32 v147, v147, v38, v39
	v_max3_f32 v126, v126, v55, v56
	v_max3_f32 v147, v147, v40, v41
	v_max3_f32 v126, v126, v57, v58
	v_max3_f32 v147, v147, v42, v43
	v_max3_f32 v126, v126, v59, v60
	v_max3_f32 v147, v147, v44, v45
	v_max3_f32 v126, v126, v61, v62
	v_max3_f32 v147, v147, v46, v47
	v_max3_f32 v126, v126, v63, v147
	s_nop 0
	v_mov_b32_e32 v147, v126
	v_mov_b32_e32 v150, v126
	s_nop 1
	v_permlane32_swap_b32 v147, v150
	s_nop 1
	v_max3_f32 v147, v149, v147, v150
	v_sub_f32_e32 v126, v149, v147
	v_exp_f32_e32 v126, v126
	v_cmp_gt_f32_e32 vcc, v147, v149
	s_cbranch_vccz .LBB0_292
	v_pk_mul_f32 v[30:31], v[30:31], v[126:127] op_sel_hi:[1,0]
	v_pk_mul_f32 v[28:29], v[28:29], v[126:127] op_sel_hi:[1,0]
	v_pk_mul_f32 v[26:27], v[26:27], v[126:127] op_sel_hi:[1,0]
	v_pk_mul_f32 v[24:25], v[24:25], v[126:127] op_sel_hi:[1,0]
	v_pk_mul_f32 v[22:23], v[22:23], v[126:127] op_sel_hi:[1,0]
	v_pk_mul_f32 v[20:21], v[20:21], v[126:127] op_sel_hi:[1,0]
	v_pk_mul_f32 v[18:19], v[18:19], v[126:127] op_sel_hi:[1,0]
	v_pk_mul_f32 v[16:17], v[16:17], v[126:127] op_sel_hi:[1,0]
	v_pk_mul_f32 v[14:15], v[14:15], v[126:127] op_sel_hi:[1,0]
	v_pk_mul_f32 v[12:13], v[12:13], v[126:127] op_sel_hi:[1,0]
	v_pk_mul_f32 v[10:11], v[10:11], v[126:127] op_sel_hi:[1,0]
	v_pk_mul_f32 v[8:9], v[8:9], v[126:127] op_sel_hi:[1,0]
	v_pk_mul_f32 v[6:7], v[6:7], v[126:127] op_sel_hi:[1,0]
	v_pk_mul_f32 v[4:5], v[4:5], v[126:127] op_sel_hi:[1,0]
	v_pk_mul_f32 v[2:3], v[2:3], v[126:127] op_sel_hi:[1,0]
	v_pk_mul_f32 v[0:1], v[0:1], v[126:127] op_sel_hi:[1,0]
